# split-K tail units (phases 6/9): write-through partial stores + system-scope partial loads instead of per-WG L2 writeback/invalidate, single polling wave
# speedup vs baseline: 1.0361x; 1.0104x over previous
.Lres_split_p9:
	s_sub_i32 s3, s12, 0x100
	s_mul_i32 s26, s3, 0x1746
	s_lshr_b32 s26, s26, 16
	s_mul_i32 s32, s26, 11
	s_sub_i32 s32, s3, s32
	s_lshl_b32 s38, s3, 18
	s_add_u32 s22, s44, s38
	s_addc_u32 s23, s45, 0
	s_add_u32 s22, s22, 0x2200000
	s_addc_u32 s23, s23, 0
	s_mul_i32 s38, s26, 0x2c0000
	s_add_u32 s24, s44, s38
	s_addc_u32 s25, s45, 0
	s_add_u32 s24, s24, 0x2200000
	s_addc_u32 s25, s25, 0
	s_lshl_b32 s38, s26, 2
	s_add_u32 s4, s46, s38
	s_addc_u32 s5, s47, 0
	s_add_u32 s4, s4, 0xdacbc20
	s_addc_u32 s5, s5, 0
	v_lshlrev_b32_e32 v160, 5, v145
	v_lshl_or_b32 v160, v146, 2, v160
	v_lshlrev_b32_e32 v160, 2, v160
	v_lshl_add_u32 v237, v147, 10, v160
	v_mov_b32_e32 v160, v237
	global_store_dwordx4 v160, v[124:127], s[22:23] sc0 sc1
	global_store_dwordx4 v160, v[120:123], s[22:23] offset:64 sc0 sc1
	global_store_dwordx4 v160, v[116:119], s[22:23] offset:512 sc0 sc1
	global_store_dwordx4 v160, v[112:115], s[22:23] offset:576 sc0 sc1
	v_add_u32_e32 v160, 0x4000, v237
	global_store_dwordx4 v160, v[108:111], s[22:23] sc0 sc1
	global_store_dwordx4 v160, v[104:107], s[22:23] offset:64 sc0 sc1
	global_store_dwordx4 v160, v[100:103], s[22:23] offset:512 sc0 sc1
	global_store_dwordx4 v160, v[96:99], s[22:23] offset:576 sc0 sc1
	v_add_u32_e32 v160, 0x8000, v237
	global_store_dwordx4 v160, v[92:95], s[22:23] sc0 sc1
	global_store_dwordx4 v160, v[88:91], s[22:23] offset:64 sc0 sc1
	global_store_dwordx4 v160, v[84:87], s[22:23] offset:512 sc0 sc1
	global_store_dwordx4 v160, v[80:83], s[22:23] offset:576 sc0 sc1
	v_add_u32_e32 v160, 0xc000, v237
	global_store_dwordx4 v160, v[76:79], s[22:23] sc0 sc1
	global_store_dwordx4 v160, v[72:75], s[22:23] offset:64 sc0 sc1
	global_store_dwordx4 v160, v[68:71], s[22:23] offset:512 sc0 sc1
	global_store_dwordx4 v160, v[64:67], s[22:23] offset:576 sc0 sc1
	v_add_u32_e32 v160, 0x20000, v237
	global_store_dwordx4 v160, v[60:63], s[22:23] sc0 sc1
	global_store_dwordx4 v160, v[56:59], s[22:23] offset:64 sc0 sc1
	global_store_dwordx4 v160, v[52:55], s[22:23] offset:512 sc0 sc1
	global_store_dwordx4 v160, v[48:51], s[22:23] offset:576 sc0 sc1
	v_add_u32_e32 v160, 0x24000, v237
	global_store_dwordx4 v160, v[44:47], s[22:23] sc0 sc1
	global_store_dwordx4 v160, v[40:43], s[22:23] offset:64 sc0 sc1
	global_store_dwordx4 v160, v[36:39], s[22:23] offset:512 sc0 sc1
	global_store_dwordx4 v160, v[32:35], s[22:23] offset:576 sc0 sc1
	v_add_u32_e32 v160, 0x28000, v237
	global_store_dwordx4 v160, v[28:31], s[22:23] sc0 sc1
	global_store_dwordx4 v160, v[24:27], s[22:23] offset:64 sc0 sc1
	global_store_dwordx4 v160, v[20:23], s[22:23] offset:512 sc0 sc1
	global_store_dwordx4 v160, v[16:19], s[22:23] offset:576 sc0 sc1
	v_add_u32_e32 v160, 0x2c000, v237
	global_store_dwordx4 v160, v[12:15], s[22:23] sc0 sc1
	global_store_dwordx4 v160, v[8:11], s[22:23] offset:64 sc0 sc1
	global_store_dwordx4 v160, v[4:7], s[22:23] offset:512 sc0 sc1
	global_store_dwordx4 v160, v[0:3], s[22:23] offset:576 sc0 sc1
	s_waitcnt vmcnt(0)
	s_barrier
	v_mov_b32_e32 v238, 0
	s_cmp_lg_u32 s48, 0
	s_cbranch_scc1 .Lres_nosig_p9
	v_mov_b32_e32 v236, 1
	s_mov_b64 exec, 1
	global_atomic_add v238, v236, s[4:5]
	s_mov_b64 exec, -1
	s_mov_b32 s98, 0

.Lres_go_p9:
.Lres_nosig_p9:
	s_barrier
	v_mbcnt_lo_u32_b32 v232, -1, 0
	v_mbcnt_hi_u32_b32 v232, -1, v232
	v_lshlrev_b32_e32 v232, 4, v232
	s_lshl_b32 s3, s21, 10
	v_add_u32_e32 v233, s3, v232
	global_load_dwordx4 v[128:131], v233, s[0:1]
	s_lshr_b32 s38, s48, 6
	s_mul_i32 s57, s32, 24
	s_add_i32 s99, s57, 24
	s_min_u32 s99, s99, 0x100
	s_add_i32 s57, s57, s38
.Lres_rloop_p9:
	s_cmp_ge_u32 s57, s99
	s_cbranch_scc1 .Lres_end_p9
	s_add_i32 s38, s57, 0
	s_lshl_b32 s98, s38, 10
	v_add_u32_e32 v234, s98, v232
	s_mov_b64 s[22:23], s[24:25]
	global_load_dwordx4 v[144:147], v234, s[22:23] sc0 sc1
	s_add_u32 s22, s22, 0x40000
	s_addc_u32 s23, s23, 0
	global_load_dwordx4 v[148:151], v234, s[22:23] sc0 sc1
	s_add_u32 s22, s22, 0x40000
	s_addc_u32 s23, s23, 0
	global_load_dwordx4 v[152:155], v234, s[22:23] sc0 sc1
	s_add_u32 s22, s22, 0x40000
	s_addc_u32 s23, s23, 0
	global_load_dwordx4 v[156:159], v234, s[22:23] sc0 sc1
	s_add_u32 s22, s22, 0x40000
	s_addc_u32 s23, s23, 0
	global_load_dwordx4 v[164:167], v234, s[22:23] sc0 sc1
	s_add_u32 s22, s22, 0x40000
	s_addc_u32 s23, s23, 0
	global_load_dwordx4 v[168:171], v234, s[22:23] sc0 sc1
	s_add_u32 s22, s22, 0x40000
	s_addc_u32 s23, s23, 0
	global_load_dwordx4 v[172:175], v234, s[22:23] sc0 sc1
	s_add_u32 s22, s22, 0x40000
	s_addc_u32 s23, s23, 0
	global_load_dwordx4 v[198:201], v234, s[22:23] sc0 sc1
	s_add_u32 s22, s22, 0x40000
	s_addc_u32 s23, s23, 0
	global_load_dwordx4 v[202:205], v234, s[22:23] sc0 sc1
	s_add_u32 s22, s22, 0x40000
	s_addc_u32 s23, s23, 0
	global_load_dwordx4 v[206:209], v234, s[22:23] sc0 sc1
	s_add_u32 s22, s22, 0x40000
	s_addc_u32 s23, s23, 0
	global_load_dwordx4 v[210:213], v234, s[22:23] sc0 sc1
	s_add_i32 s38, s38, s20
	s_lshl_b32 s38, s38, 12
	s_add_i32 s38, s38, s3
	v_add_u32_e32 v235, s38, v232
	global_load_dwordx4 v[214:217], v235, s[8:9]
	s_waitcnt vmcnt(0)
	v_pk_add_f32 v[144:145], v[144:145], v[148:149]
	v_pk_add_f32 v[146:147], v[146:147], v[150:151]
	v_pk_add_f32 v[144:145], v[144:145], v[152:153]
	v_pk_add_f32 v[146:147], v[146:147], v[154:155]
	v_pk_add_f32 v[144:145], v[144:145], v[156:157]
	v_pk_add_f32 v[146:147], v[146:147], v[158:159]
	v_pk_add_f32 v[144:145], v[144:145], v[164:165]
	v_pk_add_f32 v[146:147], v[146:147], v[166:167]
	v_pk_add_f32 v[144:145], v[144:145], v[168:169]
	v_pk_add_f32 v[146:147], v[146:147], v[170:171]
	v_pk_add_f32 v[144:145], v[144:145], v[172:173]
	v_pk_add_f32 v[146:147], v[146:147], v[174:175]
	v_pk_add_f32 v[144:145], v[144:145], v[198:199]
	v_pk_add_f32 v[146:147], v[146:147], v[200:201]
	v_pk_add_f32 v[144:145], v[144:145], v[202:203]
	v_pk_add_f32 v[146:147], v[146:147], v[204:205]
	v_pk_add_f32 v[144:145], v[144:145], v[206:207]
	v_pk_add_f32 v[146:147], v[146:147], v[208:209]
	v_pk_add_f32 v[144:145], v[144:145], v[210:211]
	v_pk_add_f32 v[146:147], v[146:147], v[212:213]
	v_pk_fma_f32 v[144:145], v[144:145], v[128:129], v[214:215]
	v_pk_fma_f32 v[146:147], v[146:147], v[130:131], v[216:217]
	global_store_dwordx4 v235, v[144:147], s[8:9]
	s_add_i32 s57, s57, 8
	s_branch .Lres_rloop_p9

.Lres_split_p6:
	s_sub_i32 s3, s23, 0x100
	s_lshr_b32 s5, s3, 2
	s_and_b32 s32, s3, 3
	s_lshl_b32 s36, s3, 18
	s_add_u32 s20, s44, s36
	s_addc_u32 s21, s45, 0
	s_add_u32 s20, s20, 0x2200000
	s_addc_u32 s21, s21, 0
	s_mul_i32 s36, s5, 0x100000
	s_add_u32 s34, s44, s36
	s_addc_u32 s35, s45, 0
	s_add_u32 s34, s34, 0x2200000
	s_addc_u32 s35, s35, 0
	s_lshl_b32 s36, s5, 2
	s_add_u32 s98, s46, s36
	s_addc_u32 s99, s47, 0
	s_add_u32 s98, s98, 0xdacbc00
	s_addc_u32 s99, s99, 0
	v_lshlrev_b32_e32 v160, 5, v145
	v_lshl_or_b32 v160, v146, 2, v160
	v_lshlrev_b32_e32 v160, 2, v160
	v_lshl_add_u32 v237, v147, 10, v160
	v_mov_b32_e32 v160, v237
	global_store_dwordx4 v160, v[124:127], s[20:21] sc0 sc1
	global_store_dwordx4 v160, v[120:123], s[20:21] offset:64 sc0 sc1
	global_store_dwordx4 v160, v[116:119], s[20:21] offset:512 sc0 sc1
	global_store_dwordx4 v160, v[112:115], s[20:21] offset:576 sc0 sc1
	v_add_u32_e32 v160, 0x4000, v237
	global_store_dwordx4 v160, v[108:111], s[20:21] sc0 sc1
	global_store_dwordx4 v160, v[104:107], s[20:21] offset:64 sc0 sc1
	global_store_dwordx4 v160, v[100:103], s[20:21] offset:512 sc0 sc1
	global_store_dwordx4 v160, v[96:99], s[20:21] offset:576 sc0 sc1
	v_add_u32_e32 v160, 0x8000, v237
	global_store_dwordx4 v160, v[92:95], s[20:21] sc0 sc1
	global_store_dwordx4 v160, v[88:91], s[20:21] offset:64 sc0 sc1
	global_store_dwordx4 v160, v[84:87], s[20:21] offset:512 sc0 sc1
	global_store_dwordx4 v160, v[80:83], s[20:21] offset:576 sc0 sc1
	v_add_u32_e32 v160, 0xc000, v237
	global_store_dwordx4 v160, v[76:79], s[20:21] sc0 sc1
	global_store_dwordx4 v160, v[72:75], s[20:21] offset:64 sc0 sc1
	global_store_dwordx4 v160, v[68:71], s[20:21] offset:512 sc0 sc1
	global_store_dwordx4 v160, v[64:67], s[20:21] offset:576 sc0 sc1
	v_add_u32_e32 v160, 0x20000, v237
	global_store_dwordx4 v160, v[60:63], s[20:21] sc0 sc1
	global_store_dwordx4 v160, v[56:59], s[20:21] offset:64 sc0 sc1
	global_store_dwordx4 v160, v[52:55], s[20:21] offset:512 sc0 sc1
	global_store_dwordx4 v160, v[48:51], s[20:21] offset:576 sc0 sc1
	v_add_u32_e32 v160, 0x24000, v237
	global_store_dwordx4 v160, v[44:47], s[20:21] sc0 sc1
	global_store_dwordx4 v160, v[40:43], s[20:21] offset:64 sc0 sc1
	global_store_dwordx4 v160, v[36:39], s[20:21] offset:512 sc0 sc1
	global_store_dwordx4 v160, v[32:35], s[20:21] offset:576 sc0 sc1
	v_add_u32_e32 v160, 0x28000, v237
	global_store_dwordx4 v160, v[28:31], s[20:21] sc0 sc1
	global_store_dwordx4 v160, v[24:27], s[20:21] offset:64 sc0 sc1
	global_store_dwordx4 v160, v[20:23], s[20:21] offset:512 sc0 sc1
	global_store_dwordx4 v160, v[16:19], s[20:21] offset:576 sc0 sc1
	v_add_u32_e32 v160, 0x2c000, v237
	global_store_dwordx4 v160, v[12:15], s[20:21] sc0 sc1
	global_store_dwordx4 v160, v[8:11], s[20:21] offset:64 sc0 sc1
	global_store_dwordx4 v160, v[4:7], s[20:21] offset:512 sc0 sc1
	global_store_dwordx4 v160, v[0:3], s[20:21] offset:576 sc0 sc1
	s_waitcnt vmcnt(0)
	s_barrier
	v_mov_b32_e32 v238, 0
	s_cmp_lg_u32 s48, 0
	s_cbranch_scc1 .Lres_nosig_p6
	v_mov_b32_e32 v236, 1
	s_mov_b64 exec, 1
	global_atomic_add v238, v236, s[98:99]
	s_mov_b64 exec, -1
	s_mov_b32 s67, 0

.Lres_go_p6:
.Lres_nosig_p6:
	s_barrier
	v_mbcnt_lo_u32_b32 v232, -1, 0
	v_mbcnt_hi_u32_b32 v232, -1, v232
	v_lshlrev_b32_e32 v232, 4, v232
	s_lshl_b32 s3, s10, 2
	v_add_u32_e32 v233, s3, v232
	global_load_dwordx4 v[128:131], v233, s[0:1]
	s_lshr_b32 s36, s48, 6
	s_mul_i32 s38, s32, 64
	s_add_i32 s57, s38, 64
	s_min_u32 s57, s57, 0x100
	s_add_i32 s38, s38, s36
.Lres_rloop_p6:
	s_cmp_ge_u32 s38, s57
	s_cbranch_scc1 .Lres_end_p6
	s_add_i32 s36, s38, 0
	s_lshl_b32 s67, s36, 10
	v_add_u32_e32 v234, s67, v232
	s_mov_b64 s[20:21], s[34:35]
	global_load_dwordx4 v[144:147], v234, s[20:21] sc0 sc1
	s_add_u32 s20, s20, 0x40000
	s_addc_u32 s21, s21, 0
	global_load_dwordx4 v[148:151], v234, s[20:21] sc0 sc1
	s_add_u32 s20, s20, 0x40000
	s_addc_u32 s21, s21, 0
	global_load_dwordx4 v[152:155], v234, s[20:21] sc0 sc1
	s_add_u32 s20, s20, 0x40000
	s_addc_u32 s21, s21, 0
	global_load_dwordx4 v[156:159], v234, s[20:21] sc0 sc1
	s_add_i32 s36, s36, s4
	s_lshl_b32 s36, s36, 12
	s_add_i32 s36, s36, s3
	v_add_u32_e32 v235, s36, v232
	global_load_dwordx4 v[164:167], v235, s[12:13]
	s_add_i32 s36, s38, 8
	s_lshl_b32 s67, s36, 10
	v_add_u32_e32 v234, s67, v232
	s_mov_b64 s[20:21], s[34:35]
	global_load_dwordx4 v[168:171], v234, s[20:21] sc0 sc1
	s_add_u32 s20, s20, 0x40000
	s_addc_u32 s21, s21, 0
	global_load_dwordx4 v[172:175], v234, s[20:21] sc0 sc1
	s_add_u32 s20, s20, 0x40000
	s_addc_u32 s21, s21, 0
	global_load_dwordx4 v[198:201], v234, s[20:21] sc0 sc1
	s_add_u32 s20, s20, 0x40000
	s_addc_u32 s21, s21, 0
	global_load_dwordx4 v[202:205], v234, s[20:21] sc0 sc1
	s_add_i32 s36, s36, s4
	s_lshl_b32 s36, s36, 12
	s_add_i32 s36, s36, s3
	v_add_u32_e32 v237, s36, v232
	global_load_dwordx4 v[206:209], v237, s[12:13]
	s_waitcnt vmcnt(0)
	v_pk_add_f32 v[144:145], v[144:145], v[148:149]
	v_pk_add_f32 v[146:147], v[146:147], v[150:151]
	v_pk_add_f32 v[144:145], v[144:145], v[152:153]
	v_pk_add_f32 v[146:147], v[146:147], v[154:155]
	v_pk_add_f32 v[144:145], v[144:145], v[156:157]
	v_pk_add_f32 v[146:147], v[146:147], v[158:159]
	v_pk_fma_f32 v[144:145], v[144:145], v[128:129], v[164:165]
	v_pk_fma_f32 v[146:147], v[146:147], v[130:131], v[166:167]
	global_store_dwordx4 v235, v[144:147], s[12:13]
	v_pk_add_f32 v[168:169], v[168:169], v[172:173]
	v_pk_add_f32 v[170:171], v[170:171], v[174:175]
	v_pk_add_f32 v[168:169], v[168:169], v[198:199]
	v_pk_add_f32 v[170:171], v[170:171], v[200:201]
	v_pk_add_f32 v[168:169], v[168:169], v[202:203]
	v_pk_add_f32 v[170:171], v[170:171], v[204:205]
	v_pk_fma_f32 v[168:169], v[168:169], v[128:129], v[206:207]
	v_pk_fma_f32 v[170:171], v[170:171], v[130:131], v[208:209]
	global_store_dwordx4 v237, v[168:171], s[12:13]
	s_add_i32 s38, s38, 16
	s_branch .Lres_rloop_p6
